# GEMM: per-unit accumulator zeroing with 64-bit moves; FFN1 epilogue store addresses as base plus constant offsets
# baseline (speedup 1.0000x reference)
; template <class Epi, class Sched, bool ALIGN_EPI = false, bool SP2 = false>
; __device__ __forceinline__ void gemm_phase(PG8_LAS unsigned char* lds, const Gemm g, const Sched& S, const Epi& E) {
;     ...
;         const char* nA = has_next ? (const char*)g.A + (size_t)nxt.pm * tstepA + (size_t)(nxt.pn / g.adiv) * g.aoff * 2 : cA; const char* nB = has_next ? (const char*)g.Bt + (size_t)nxt.pn * tstepB : cB;
;         for (int t = 0; t < nt; t += 2) {
;             const bool last = (t == nt - 2);
;             const char* a1 = cA + (size_t)(t + 1) * kstep;
;             const char* a2 = last ? nA : cA + (size_t)(t + 2) * kstep; const char* b2 = last ? nB : cB + (size_t)(t + 2) * kstep;
;             const char* a3 = a2 + kstep; const char* b3 = b2 + kstep;
;     ...
; #pragma unroll
;         for (int a = 0; a < 2; ++a)
; #pragma unroll
;             for (int b = 0; b < 2; ++b)
; #pragma unroll
;                 for (int m = 0; m < 4; ++m)
; #pragma unroll
;                     for (int n = 0; n < 2; ++n) acc[a][b][m][n] = (f32x4){0.f, 0.f, 0.f, 0.f};
;         cur = nxt; cA = nA; cB = nB; ++ui;
.LBB0_254:
	s_ashr_i32 s9, s8, 31
	s_lshl_b64 s[10:11], s[8:9], 19
	s_add_u32 s10, s92, s10
	s_addc_u32 s11, s93, s11
	s_and_b64 s[12:13], s[0:1], exec
	s_cselect_b32 s9, s11, s15
	s_cselect_b32 s34, s10, s14
	s_ashr_i32 s7, s6, 31
	s_lshl_b64 s[12:13], s[6:7], 19
	s_add_u32 s12, s20, s12
	s_addc_u32 s13, s22, s13
	s_and_b64 s[18:19], s[0:1], exec
	s_cselect_b32 s7, s13, s17
	s_cselect_b32 s35, s12, s16
	s_add_u32 s14, s14, 0x40080
	s_addc_u32 s15, s15, 0
	s_add_u32 s37, s16, 0x100
	v_mov_b64_e32 v[2:3], 0
	s_addc_u32 s38, s17, 0
	s_mov_b32 s39, -2
	v_mov_b64_e32 v[4:5], 0
	v_mov_b64_e32 v[10:11], 0
	v_mov_b64_e32 v[12:13], 0
	v_mov_b64_e32 v[18:19], 0
	v_mov_b64_e32 v[20:21], 0
	v_mov_b64_e32 v[26:27], 0
	v_mov_b64_e32 v[28:29], 0
	v_mov_b64_e32 v[34:35], 0
	v_mov_b64_e32 v[36:37], 0
	v_mov_b64_e32 v[42:43], 0
	v_mov_b64_e32 v[44:45], 0
	v_mov_b64_e32 v[50:51], 0
	s_waitcnt vmcnt(0)
	v_mov_b64_e32 v[52:53], 0
	v_mov_b64_e32 v[58:59], 0
	v_mov_b64_e32 v[60:61], 0
	v_mov_b64_e32 v[6:7], 0
	v_mov_b64_e32 v[8:9], 0
	v_mov_b64_e32 v[14:15], 0
	v_mov_b64_e32 v[16:17], 0
	v_mov_b64_e32 v[22:23], 0
	v_mov_b64_e32 v[24:25], 0
	v_mov_b64_e32 v[30:31], 0
	v_mov_b64_e32 v[32:33], 0
	v_mov_b64_e32 v[38:39], 0
	v_mov_b64_e32 v[40:41], 0
	v_mov_b64_e32 v[46:47], 0
	v_mov_b64_e32 v[48:49], 0
	v_mov_b64_e32 v[54:55], 0
	v_mov_b64_e32 v[56:57], 0
	v_mov_b64_e32 v[62:63], 0
	v_mov_b64_e32 v[64:65], 0
	v_mov_b64_e32 v[66:67], 0
	v_mov_b64_e32 v[68:69], 0
	v_mov_b64_e32 v[74:75], 0
	v_mov_b64_e32 v[76:77], 0
	v_mov_b64_e32 v[82:83], 0
	v_mov_b64_e32 v[84:85], 0
	v_mov_b64_e32 v[90:91], 0
	v_mov_b64_e32 v[92:93], 0
	v_mov_b64_e32 v[98:99], 0
	v_mov_b64_e32 v[100:101], 0
	v_mov_b64_e32 v[106:107], 0
	v_mov_b64_e32 v[108:109], 0
	v_mov_b64_e32 v[114:115], 0
	v_mov_b64_e32 v[116:117], 0
	v_mov_b64_e32 v[122:123], 0
	v_mov_b64_e32 v[124:125], 0
	v_mov_b64_e32 v[70:71], 0
	v_mov_b64_e32 v[72:73], 0
	v_mov_b64_e32 v[78:79], 0
	v_mov_b64_e32 v[80:81], 0
	v_mov_b64_e32 v[86:87], 0
	v_mov_b64_e32 v[88:89], 0
	v_mov_b64_e32 v[94:95], 0
	v_mov_b64_e32 v[96:97], 0
	v_mov_b64_e32 v[102:103], 0
	v_mov_b64_e32 v[104:105], 0
	v_mov_b64_e32 v[110:111], 0
	v_mov_b64_e32 v[112:113], 0
	v_mov_b64_e32 v[118:119], 0
	v_mov_b64_e32 v[120:121], 0
	v_mov_b64_e32 v[126:127], 0
	v_mov_b64_e32 v[128:129], 0

; __device__ __forceinline__ float sigm(float x) { return __builtin_amdgcn_rcpf(1.f + __builtin_amdgcn_exp2f(-1.4426950408889634f * x)); }
; __device__ __forceinline__ u32x4v pack8(f32x4 a, f32x4 b) { u32x4v o; o.x = cvt_pk_bf16(a[0], a[1]); o.y = cvt_pk_bf16(a[2], a[3]); o.z = cvt_pk_bf16(b[0], b[1]); o.w = cvt_pk_bf16(b[2], b[3]); return o; }
;     __device__ __forceinline__ void operator()(const f32x4 (&acc)[2][2][4][2], const pg8::Unit& u, int wr, int wc, int fr, int fq) const {
; #pragma unroll
;         for (int ai = 0; ai < 2; ++ai)
; #pragma unroll
;             for (int m = 0; m < 4; ++m) { const int row = u.pm * 256 + ai * 128 + wr * 64 + m * 16 + fr;
;                 f32x4 o[2];
; #pragma unroll
;                 for (int n = 0; n < 2; ++n) { const f32x4 g = acc[ai][0][m][n], uu = acc[ai][1][m][n];
; #pragma unroll
;                     for (int j = 0; j < 4; ++j) o[n][j] = g[j] * sigm(g[j]) * uu[j]; }
;                 *(u32x4v*)(O + (size_t)row * DFF + u.pn * 128 + wc * 32 + fq * 8) = pack8(o[0], o[1]); }
;     }
.LBB0_258:
	v_mul_f32_e32 v148, 0xbfb8aa3b, v126
	v_mul_f32_e32 v149, 0xbfb8aa3b, v127
	v_exp_f32_e32 v148, v148
	v_exp_f32_e32 v149, v149
	v_readlane_b32 s14, v252, 35
	s_lshl_b32 s7, s33, 8
	v_add_f32_e32 v148, 1.0, v148
	v_add_f32_e32 v149, 1.0, v149
	v_rcp_f32_e32 v148, v148
	v_rcp_f32_e32 v149, v149
	v_readlane_b32 s15, v252, 36
	s_movk_i32 s9, 0x1600
	v_readlane_b32 s18, v253, 61
	v_pk_mul_f32 v[126:127], v[126:127], v[148:149]
	v_readlane_b32 s19, v253, 62
	v_pk_mul_f32 v[122:123], v[126:127], v[122:123]
	v_mul_f32_e32 v126, 0xbfb8aa3b, v128
	v_mul_f32_e32 v127, 0xbfb8aa3b, v129
	v_exp_f32_e32 v126, v126
	v_exp_f32_e32 v127, v127
	s_andn2_b64 vcc, exec, s[0:1]
	s_movk_i32 s34, 0x4000
	v_add_f32_e32 v126, 1.0, v126
	v_add_f32_e32 v127, 1.0, v127
	v_rcp_f32_e32 v126, v126
	v_rcp_f32_e32 v127, v127
	s_mov_b32 s35, 0x8000
	s_mov_b32 s36, 0xf149f2ca
	s_mov_b32 s38, 0x358637bd
	v_pk_mul_f32 v[126:127], v[128:129], v[126:127]
	s_nop 0
	v_pk_mul_f32 v[124:125], v[126:127], v[124:125]
	v_mul_f32_e32 v126, 0xbfb8aa3b, v118
	v_mul_f32_e32 v127, 0xbfb8aa3b, v119
	v_exp_f32_e32 v126, v126
	v_exp_f32_e32 v127, v127
	v_add_f32_e32 v126, 1.0, v126
	v_add_f32_e32 v127, 1.0, v127
	v_rcp_f32_e32 v126, v126
	v_rcp_f32_e32 v127, v127
	s_nop 0
	v_pk_mul_f32 v[118:119], v[118:119], v[126:127]
	s_nop 0
	v_pk_mul_f32 v[114:115], v[118:119], v[114:115]
	v_mul_f32_e32 v118, 0xbfb8aa3b, v120
	v_mul_f32_e32 v119, 0xbfb8aa3b, v121
	v_exp_f32_e32 v118, v118
	v_exp_f32_e32 v119, v119
	v_add_f32_e32 v118, 1.0, v118
	v_add_f32_e32 v119, 1.0, v119
	v_rcp_f32_e32 v118, v118
	v_rcp_f32_e32 v119, v119
	s_nop 0
	v_pk_mul_f32 v[118:119], v[120:121], v[118:119]
	s_nop 0
	v_pk_mul_f32 v[126:127], v[118:119], v[116:117]
	v_add_u32_e32 v116, s7, v142
	v_cvt_pk_bf16_f32 v120, v114, v115
	v_mov_b64_e32 v[114:115], s[14:15]
	v_cvt_pk_bf16_f32 v118, v122, v123
	v_mad_i64_i32 v[122:123], s[14:15], v116, s9, v[114:115]
	s_lshl_b32 s14, s31, 7
	v_mul_f32_e32 v117, 0xbfb8aa3b, v110
	s_ashr_i32 s15, s14, 31
	v_exp_f32_e32 v117, v117
	s_lshl_b64 s[14:15], s[14:15], 1
	v_lshl_add_u64 v[122:123], v[122:123], 0, s[14:15]
	v_lshl_add_u64 v[122:123], v[122:123], 0, s[18:19]
	v_cvt_pk_bf16_f32 v119, v124, v125
	v_cvt_pk_bf16_f32 v121, v126, v127
	v_lshl_add_u64 v[122:123], v[122:123], 0, v[0:1]
	v_add_f32_e32 v117, 1.0, v117
	global_store_dwordx4 v[122:123], v[118:121], off
	s_nop 1
	v_rcp_f32_e32 v118, v117
	v_mul_f32_e32 v117, 0xbfb8aa3b, v111
	v_exp_f32_e32 v117, v117
	s_nop 0
	v_add_f32_e32 v117, 1.0, v117
	v_rcp_f32_e32 v119, v117
	s_nop 0
	v_pk_mul_f32 v[110:111], v[110:111], v[118:119]
	s_nop 0
	v_pk_mul_f32 v[106:107], v[110:111], v[106:107]
	v_mul_f32_e32 v110, 0xbfb8aa3b, v112
	v_mul_f32_e32 v111, 0xbfb8aa3b, v113
	v_exp_f32_e32 v110, v110
	v_exp_f32_e32 v111, v111
	v_add_f32_e32 v110, 1.0, v110
	v_add_f32_e32 v111, 1.0, v111
	v_rcp_f32_e32 v110, v110
	v_rcp_f32_e32 v111, v111
	s_nop 0
	v_pk_mul_f32 v[110:111], v[112:113], v[110:111]
	s_nop 0
	v_pk_mul_f32 v[108:109], v[110:111], v[108:109]
	v_mul_f32_e32 v110, 0xbfb8aa3b, v102
	v_mul_f32_e32 v111, 0xbfb8aa3b, v103
	v_exp_f32_e32 v110, v110
	v_exp_f32_e32 v111, v111
	v_add_f32_e32 v110, 1.0, v110
	v_add_f32_e32 v111, 1.0, v111
	v_rcp_f32_e32 v110, v110
	v_rcp_f32_e32 v111, v111
	s_nop 0
	v_pk_mul_f32 v[102:103], v[102:103], v[110:111]
	s_nop 0
	v_pk_mul_f32 v[102:103], v[102:103], v[98:99]
	v_mul_f32_e32 v98, 0xbfb8aa3b, v104
	v_mul_f32_e32 v99, 0xbfb8aa3b, v105
	v_exp_f32_e32 v98, v98
	v_exp_f32_e32 v99, v99
	v_add_f32_e32 v98, 1.0, v98
	v_add_f32_e32 v99, 1.0, v99
	v_rcp_f32_e32 v98, v98
	v_rcp_f32_e32 v99, v99
	s_nop 0
	v_pk_mul_f32 v[98:99], v[104:105], v[98:99]
	s_nop 0
	v_pk_mul_f32 v[104:105], v[98:99], v[100:101]
	v_cvt_pk_bf16_f32 v100, v102, v103
	v_cvt_pk_bf16_f32 v98, v106, v107
	v_cvt_pk_bf16_f32 v99, v108, v109
	v_cvt_pk_bf16_f32 v101, v104, v105
	s_mov_b32 s16, 0x16000
	s_mov_b32 s17, 0
	v_lshl_add_u64 v[102:103], s[16:17], 0, v[122:123]
	global_store_dwordx4 v[102:103], v[98:101], off
	s_nop 1
	v_mul_f32_e32 v98, 0xbfb8aa3b, v94
	v_mul_f32_e32 v99, 0xbfb8aa3b, v95
	v_exp_f32_e32 v98, v98
	v_exp_f32_e32 v99, v99
	v_add_f32_e32 v98, 1.0, v98
	v_add_f32_e32 v99, 1.0, v99
	v_rcp_f32_e32 v98, v98
	v_rcp_f32_e32 v99, v99
	s_nop 0
	v_pk_mul_f32 v[94:95], v[94:95], v[98:99]
	s_nop 0
	v_pk_mul_f32 v[90:91], v[94:95], v[90:91]
	v_mul_f32_e32 v94, 0xbfb8aa3b, v96
	v_mul_f32_e32 v95, 0xbfb8aa3b, v97
	v_exp_f32_e32 v94, v94
	v_exp_f32_e32 v95, v95
	v_add_f32_e32 v94, 1.0, v94
	v_add_f32_e32 v95, 1.0, v95
	v_rcp_f32_e32 v94, v94
	v_rcp_f32_e32 v95, v95
	s_nop 0
	v_pk_mul_f32 v[94:95], v[96:97], v[94:95]
	s_nop 0
	v_pk_mul_f32 v[92:93], v[94:95], v[92:93]
	v_mul_f32_e32 v94, 0xbfb8aa3b, v86
	v_mul_f32_e32 v95, 0xbfb8aa3b, v87
	v_exp_f32_e32 v94, v94
	v_exp_f32_e32 v95, v95
	v_add_f32_e32 v94, 1.0, v94
	v_add_f32_e32 v95, 1.0, v95
	v_rcp_f32_e32 v94, v94
	v_rcp_f32_e32 v95, v95
	s_nop 0
	v_pk_mul_f32 v[86:87], v[86:87], v[94:95]
	s_nop 0
	v_pk_mul_f32 v[86:87], v[86:87], v[82:83]
	v_mul_f32_e32 v82, 0xbfb8aa3b, v88
	v_mul_f32_e32 v83, 0xbfb8aa3b, v89
	v_exp_f32_e32 v82, v82
	v_exp_f32_e32 v83, v83
	v_add_f32_e32 v82, 1.0, v82
	v_add_f32_e32 v83, 1.0, v83
	v_rcp_f32_e32 v82, v82
	v_rcp_f32_e32 v83, v83
	s_nop 0
	v_pk_mul_f32 v[82:83], v[88:89], v[82:83]
	s_nop 0
	v_pk_mul_f32 v[88:89], v[82:83], v[84:85]
	v_cvt_pk_bf16_f32 v84, v86, v87
	v_cvt_pk_bf16_f32 v82, v90, v91
	v_cvt_pk_bf16_f32 v83, v92, v93
	v_cvt_pk_bf16_f32 v85, v88, v89
	s_mov_b32 s16, 0x2c000
	s_mov_b32 s17, 0
	v_lshl_add_u64 v[86:87], s[16:17], 0, v[122:123]
	global_store_dwordx4 v[86:87], v[82:85], off
	s_nop 1
	v_mul_f32_e32 v82, 0xbfb8aa3b, v78
; __device__ __forceinline__ float sigm(float x) { return __builtin_amdgcn_rcpf(1.f + __builtin_amdgcn_exp2f(-1.4426950408889634f * x)); }
; __device__ __forceinline__ u32x4v pack8(f32x4 a, f32x4 b) { u32x4v o; o.x = cvt_pk_bf16(a[0], a[1]); o.y = cvt_pk_bf16(a[2], a[3]); o.z = cvt_pk_bf16(b[0], b[1]); o.w = cvt_pk_bf16(b[2], b[3]); return o; }
;     __device__ __forceinline__ void operator()(const f32x4 (&acc)[2][2][4][2], const pg8::Unit& u, int wr, int wc, int fr, int fq) const {
; #pragma unroll
;         for (int ai = 0; ai < 2; ++ai)
; #pragma unroll
;             for (int m = 0; m < 4; ++m) { const int row = u.pm * 256 + ai * 128 + wr * 64 + m * 16 + fr;
;                 f32x4 o[2];
; #pragma unroll
;                 for (int n = 0; n < 2; ++n) { const f32x4 g = acc[ai][0][m][n], uu = acc[ai][1][m][n];
; #pragma unroll
;                     for (int j = 0; j < 4; ++j) o[n][j] = g[j] * sigm(g[j]) * uu[j]; }
;                 *(u32x4v*)(O + (size_t)row * DFF + u.pn * 128 + wc * 32 + fq * 8) = pack8(o[0], o[1]); }
;     }
	v_mul_f32_e32 v83, 0xbfb8aa3b, v79
	v_exp_f32_e32 v82, v82
	v_exp_f32_e32 v83, v83
	v_add_f32_e32 v82, 1.0, v82
	v_add_f32_e32 v83, 1.0, v83
	v_rcp_f32_e32 v82, v82
	v_rcp_f32_e32 v83, v83
	s_nop 0
	v_pk_mul_f32 v[78:79], v[78:79], v[82:83]
	s_nop 0
	v_pk_mul_f32 v[74:75], v[78:79], v[74:75]
	v_mul_f32_e32 v78, 0xbfb8aa3b, v80
	v_mul_f32_e32 v79, 0xbfb8aa3b, v81
	v_exp_f32_e32 v78, v78
	v_exp_f32_e32 v79, v79
	v_add_f32_e32 v78, 1.0, v78
	v_add_f32_e32 v79, 1.0, v79
	v_rcp_f32_e32 v78, v78
	v_rcp_f32_e32 v79, v79
	s_nop 0
	v_pk_mul_f32 v[78:79], v[80:81], v[78:79]
	s_nop 0
	v_pk_mul_f32 v[76:77], v[78:79], v[76:77]
	v_mul_f32_e32 v78, 0xbfb8aa3b, v70
	v_mul_f32_e32 v79, 0xbfb8aa3b, v71
	v_exp_f32_e32 v78, v78
	v_exp_f32_e32 v79, v79
	v_add_f32_e32 v78, 1.0, v78
	v_add_f32_e32 v79, 1.0, v79
	v_rcp_f32_e32 v78, v78
	v_rcp_f32_e32 v79, v79
	s_nop 0
	v_pk_mul_f32 v[70:71], v[70:71], v[78:79]
	s_nop 0
	v_pk_mul_f32 v[70:71], v[70:71], v[66:67]
	v_mul_f32_e32 v66, 0xbfb8aa3b, v72
	v_mul_f32_e32 v67, 0xbfb8aa3b, v73
	v_exp_f32_e32 v66, v66
	v_exp_f32_e32 v67, v67
	v_add_f32_e32 v66, 1.0, v66
	v_add_f32_e32 v67, 1.0, v67
	v_rcp_f32_e32 v66, v66
	v_rcp_f32_e32 v67, v67
	s_nop 0
	v_pk_mul_f32 v[66:67], v[72:73], v[66:67]
	s_nop 0
	v_pk_mul_f32 v[72:73], v[66:67], v[68:69]
	v_cvt_pk_bf16_f32 v68, v70, v71
	v_cvt_pk_bf16_f32 v66, v74, v75
	v_cvt_pk_bf16_f32 v67, v76, v77
	v_cvt_pk_bf16_f32 v69, v72, v73
	s_mov_b32 s16, 0x42000
	s_mov_b32 s17, 0
	v_lshl_add_u64 v[70:71], s[16:17], 0, v[122:123]
	global_store_dwordx4 v[70:71], v[66:69], off
	s_nop 1
	v_mul_f32_e32 v66, 0xbfb8aa3b, v62
	v_mul_f32_e32 v67, 0xbfb8aa3b, v63
	v_exp_f32_e32 v66, v66
	v_exp_f32_e32 v67, v67
	v_add_f32_e32 v66, 1.0, v66
	v_add_f32_e32 v67, 1.0, v67
	v_rcp_f32_e32 v66, v66
	v_rcp_f32_e32 v67, v67
	s_nop 0
	v_pk_mul_f32 v[62:63], v[62:63], v[66:67]
	s_nop 0
	v_pk_mul_f32 v[58:59], v[62:63], v[58:59]
	v_mul_f32_e32 v62, 0xbfb8aa3b, v64
	v_mul_f32_e32 v63, 0xbfb8aa3b, v65
	v_exp_f32_e32 v62, v62
	v_exp_f32_e32 v63, v63
	v_add_f32_e32 v62, 1.0, v62
	v_add_f32_e32 v63, 1.0, v63
	v_rcp_f32_e32 v62, v62
	v_rcp_f32_e32 v63, v63
	s_nop 0
	v_pk_mul_f32 v[62:63], v[64:65], v[62:63]
	s_nop 0
	v_pk_mul_f32 v[60:61], v[62:63], v[60:61]
	v_mul_f32_e32 v62, 0xbfb8aa3b, v54
	v_mul_f32_e32 v63, 0xbfb8aa3b, v55
	v_exp_f32_e32 v62, v62
	v_exp_f32_e32 v63, v63
	v_add_f32_e32 v62, 1.0, v62
	v_add_f32_e32 v63, 1.0, v63
	v_rcp_f32_e32 v62, v62
	v_rcp_f32_e32 v63, v63
	s_nop 0
	v_pk_mul_f32 v[54:55], v[54:55], v[62:63]
	s_nop 0
	v_pk_mul_f32 v[54:55], v[54:55], v[50:51]
	v_mul_f32_e32 v50, 0xbfb8aa3b, v56
	v_mul_f32_e32 v51, 0xbfb8aa3b, v57
	v_exp_f32_e32 v50, v50
	v_exp_f32_e32 v51, v51
	v_add_f32_e32 v50, 1.0, v50
	v_add_f32_e32 v51, 1.0, v51
	v_rcp_f32_e32 v50, v50
	v_rcp_f32_e32 v51, v51
	s_nop 0
	v_pk_mul_f32 v[50:51], v[56:57], v[50:51]
	s_nop 0
	v_pk_mul_f32 v[56:57], v[50:51], v[52:53]
	v_cvt_pk_bf16_f32 v52, v54, v55
	v_cvt_pk_bf16_f32 v50, v58, v59
	v_cvt_pk_bf16_f32 v51, v60, v61
	v_cvt_pk_bf16_f32 v53, v56, v57
	s_mov_b32 s16, 0xb0000
	s_mov_b32 s17, 0
	v_lshl_add_u64 v[54:55], s[16:17], 0, v[122:123]
	global_store_dwordx4 v[54:55], v[50:53], off
	s_nop 1
	v_mul_f32_e32 v50, 0xbfb8aa3b, v46
	v_mul_f32_e32 v51, 0xbfb8aa3b, v47
	v_exp_f32_e32 v50, v50
	v_exp_f32_e32 v51, v51
	v_add_f32_e32 v50, 1.0, v50
	v_add_f32_e32 v51, 1.0, v51
	v_rcp_f32_e32 v50, v50
	v_rcp_f32_e32 v51, v51
	s_nop 0
	v_pk_mul_f32 v[46:47], v[46:47], v[50:51]
	s_nop 0
	v_pk_mul_f32 v[42:43], v[46:47], v[42:43]
	v_mul_f32_e32 v46, 0xbfb8aa3b, v48
	v_mul_f32_e32 v47, 0xbfb8aa3b, v49
	v_exp_f32_e32 v46, v46
	v_exp_f32_e32 v47, v47
	v_add_f32_e32 v46, 1.0, v46
	v_add_f32_e32 v47, 1.0, v47
	v_rcp_f32_e32 v46, v46
	v_rcp_f32_e32 v47, v47
	s_nop 0
	v_pk_mul_f32 v[46:47], v[48:49], v[46:47]
	s_nop 0
	v_pk_mul_f32 v[44:45], v[46:47], v[44:45]
	v_mul_f32_e32 v46, 0xbfb8aa3b, v38
	v_mul_f32_e32 v47, 0xbfb8aa3b, v39
	v_exp_f32_e32 v46, v46
	v_exp_f32_e32 v47, v47
	v_add_f32_e32 v46, 1.0, v46
	v_add_f32_e32 v47, 1.0, v47
	v_rcp_f32_e32 v46, v46
; #define PG8_BAR __builtin_amdgcn_s_barrier()
; __device__ __forceinline__ float sigm(float x) { return __builtin_amdgcn_rcpf(1.f + __builtin_amdgcn_exp2f(-1.4426950408889634f * x)); }
; __device__ __forceinline__ u32x4v pack8(f32x4 a, f32x4 b) { u32x4v o; o.x = cvt_pk_bf16(a[0], a[1]); o.y = cvt_pk_bf16(a[2], a[3]); o.z = cvt_pk_bf16(b[0], b[1]); o.w = cvt_pk_bf16(b[2], b[3]); return o; }
; template <class Epi, class Sched, bool ALIGN_EPI = false, bool SP2 = false>
; __device__ __forceinline__ void gemm_phase(PG8_LAS unsigned char* lds, const Gemm g, const Sched& S, const Epi& E) {
;     ...
;         if constexpr (ALIGN_EPI) { if (wr == 0) PG8_BAR; }
;         if constexpr (!Epi::AFTER_DRAIN) { E(acc, cur, wr, wc, fr, fq); S.done(cur); }
;         if (!has_next) break;
; #pragma unroll
;         for (int a = 0; a < 2; ++a)
; #pragma unroll
;             for (int b = 0; b < 2; ++b)
; #pragma unroll
;                 for (int m = 0; m < 4; ++m)
; #pragma unroll
;                     for (int n = 0; n < 2; ++n) acc[a][b][m][n] = (f32x4){0.f, 0.f, 0.f, 0.f};
;         cur = nxt; cA = nA; cB = nB; ++ui;
;         if constexpr (ALIGN_EPI) { if (wr == 1) PG8_BAR; }
;     __device__ __forceinline__ void operator()(const f32x4 (&acc)[2][2][4][2], const pg8::Unit& u, int wr, int wc, int fr, int fq) const {
; #pragma unroll
;         for (int ai = 0; ai < 2; ++ai)
; #pragma unroll
;             for (int m = 0; m < 4; ++m) { const int row = u.pm * 256 + ai * 128 + wr * 64 + m * 16 + fr;
;                 f32x4 o[2];
; #pragma unroll
;                 for (int n = 0; n < 2; ++n) { const f32x4 g = acc[ai][0][m][n], uu = acc[ai][1][m][n];
; #pragma unroll
;                     for (int j = 0; j < 4; ++j) o[n][j] = g[j] * sigm(g[j]) * uu[j]; }
;                 *(u32x4v*)(O + (size_t)row * DFF + u.pn * 128 + wc * 32 + fq * 8) = pack8(o[0], o[1]); }
;     }
	v_rcp_f32_e32 v47, v47
	s_nop 0
	v_pk_mul_f32 v[38:39], v[38:39], v[46:47]
	s_nop 0
	v_pk_mul_f32 v[38:39], v[38:39], v[34:35]
	v_mul_f32_e32 v34, 0xbfb8aa3b, v40
	v_mul_f32_e32 v35, 0xbfb8aa3b, v41
	v_exp_f32_e32 v34, v34
	v_exp_f32_e32 v35, v35
	v_add_f32_e32 v34, 1.0, v34
	v_add_f32_e32 v35, 1.0, v35
	v_rcp_f32_e32 v34, v34
	v_rcp_f32_e32 v35, v35
	s_nop 0
	v_pk_mul_f32 v[34:35], v[40:41], v[34:35]
	s_nop 0
	v_pk_mul_f32 v[40:41], v[34:35], v[36:37]
	v_cvt_pk_bf16_f32 v36, v38, v39
	v_cvt_pk_bf16_f32 v34, v42, v43
	v_cvt_pk_bf16_f32 v35, v44, v45
	v_cvt_pk_bf16_f32 v37, v40, v41
	s_mov_b32 s16, 0xc6000
	s_mov_b32 s17, 0
	v_lshl_add_u64 v[38:39], s[16:17], 0, v[122:123]
	global_store_dwordx4 v[38:39], v[34:37], off
	s_nop 1
	v_mul_f32_e32 v34, 0xbfb8aa3b, v30
	v_mul_f32_e32 v35, 0xbfb8aa3b, v31
	v_exp_f32_e32 v34, v34
	v_exp_f32_e32 v35, v35
	v_add_f32_e32 v34, 1.0, v34
	v_add_f32_e32 v35, 1.0, v35
	v_rcp_f32_e32 v34, v34
	v_rcp_f32_e32 v35, v35
	s_nop 0
	v_pk_mul_f32 v[30:31], v[30:31], v[34:35]
	s_nop 0
	v_pk_mul_f32 v[26:27], v[30:31], v[26:27]
	v_mul_f32_e32 v30, 0xbfb8aa3b, v32
	v_mul_f32_e32 v31, 0xbfb8aa3b, v33
	v_exp_f32_e32 v30, v30
	v_exp_f32_e32 v31, v31
	v_add_f32_e32 v30, 1.0, v30
	v_add_f32_e32 v31, 1.0, v31
	v_rcp_f32_e32 v30, v30
	v_rcp_f32_e32 v31, v31
	s_nop 0
	v_pk_mul_f32 v[30:31], v[32:33], v[30:31]
	s_nop 0
	v_pk_mul_f32 v[28:29], v[30:31], v[28:29]
	v_mul_f32_e32 v30, 0xbfb8aa3b, v22
	v_mul_f32_e32 v31, 0xbfb8aa3b, v23
	v_exp_f32_e32 v30, v30
	v_exp_f32_e32 v31, v31
	v_add_f32_e32 v30, 1.0, v30
	v_add_f32_e32 v31, 1.0, v31
	v_rcp_f32_e32 v30, v30
	v_rcp_f32_e32 v31, v31
	s_nop 0
	v_pk_mul_f32 v[22:23], v[22:23], v[30:31]
	s_nop 0
	v_pk_mul_f32 v[22:23], v[22:23], v[18:19]
	v_mul_f32_e32 v18, 0xbfb8aa3b, v24
	v_mul_f32_e32 v19, 0xbfb8aa3b, v25
	v_exp_f32_e32 v18, v18
	v_exp_f32_e32 v19, v19
	v_add_f32_e32 v18, 1.0, v18
	v_add_f32_e32 v19, 1.0, v19
	v_rcp_f32_e32 v18, v18
	v_rcp_f32_e32 v19, v19
	s_nop 0
	v_pk_mul_f32 v[18:19], v[24:25], v[18:19]
	s_nop 0
	v_pk_mul_f32 v[24:25], v[18:19], v[20:21]
	v_cvt_pk_bf16_f32 v20, v22, v23
	v_cvt_pk_bf16_f32 v18, v26, v27
	v_cvt_pk_bf16_f32 v19, v28, v29
	v_cvt_pk_bf16_f32 v21, v24, v25
	s_mov_b32 s16, 0xdc000
	s_mov_b32 s17, 0
	v_lshl_add_u64 v[22:23], s[16:17], 0, v[122:123]
	global_store_dwordx4 v[22:23], v[18:21], off
	s_nop 1
	v_mul_f32_e32 v18, 0xbfb8aa3b, v14
	v_mul_f32_e32 v19, 0xbfb8aa3b, v15
	v_exp_f32_e32 v18, v18
	v_exp_f32_e32 v19, v19
	v_add_f32_e32 v18, 1.0, v18
	v_add_f32_e32 v19, 1.0, v19
	v_rcp_f32_e32 v18, v18
	v_rcp_f32_e32 v19, v19
	s_nop 0
	v_pk_mul_f32 v[14:15], v[14:15], v[18:19]
	s_nop 0
	v_pk_mul_f32 v[10:11], v[14:15], v[10:11]
	v_mul_f32_e32 v14, 0xbfb8aa3b, v16
	v_mul_f32_e32 v15, 0xbfb8aa3b, v17
	v_exp_f32_e32 v14, v14
	v_exp_f32_e32 v15, v15
	v_add_f32_e32 v14, 1.0, v14
	v_add_f32_e32 v15, 1.0, v15
	v_rcp_f32_e32 v14, v14
	v_rcp_f32_e32 v15, v15
	s_nop 0
	v_pk_mul_f32 v[14:15], v[16:17], v[14:15]
	s_nop 0
	v_pk_mul_f32 v[12:13], v[14:15], v[12:13]
	v_mul_f32_e32 v14, 0xbfb8aa3b, v6
	v_mul_f32_e32 v15, 0xbfb8aa3b, v7
	v_exp_f32_e32 v14, v14
	v_exp_f32_e32 v15, v15
	v_add_f32_e32 v14, 1.0, v14
	v_add_f32_e32 v15, 1.0, v15
	v_rcp_f32_e32 v14, v14
	v_rcp_f32_e32 v15, v15
	s_nop 0
	v_pk_mul_f32 v[6:7], v[6:7], v[14:15]
	s_nop 0
	v_pk_mul_f32 v[6:7], v[6:7], v[2:3]
	v_mul_f32_e32 v2, 0xbfb8aa3b, v8
	v_mul_f32_e32 v3, 0xbfb8aa3b, v9
	v_exp_f32_e32 v2, v2
	v_exp_f32_e32 v3, v3
	v_add_f32_e32 v2, 1.0, v2
	v_add_f32_e32 v3, 1.0, v3
	v_rcp_f32_e32 v2, v2
	v_rcp_f32_e32 v3, v3
	s_nop 0
	v_pk_mul_f32 v[2:3], v[8:9], v[2:3]
	s_nop 0
	v_pk_mul_f32 v[8:9], v[2:3], v[4:5]
	v_cvt_pk_bf16_f32 v4, v6, v7
	v_cvt_pk_bf16_f32 v2, v10, v11
	v_cvt_pk_bf16_f32 v3, v12, v13
	v_cvt_pk_bf16_f32 v5, v8, v9
	s_mov_b32 s16, 0xf2000
	s_mov_b32 s17, 0
	v_lshl_add_u64 v[6:7], s[16:17], 0, v[122:123]
	s_mov_b64 s[14:15], -1
	global_store_dwordx4 v[6:7], v[2:5], off
	s_cbranch_vccnz .LBB0_251
	s_andn2_b64 vcc, exec, s[2:3]
	s_cbranch_vccnz .LBB0_250
	s_barrier
	s_branch .LBB0_250

; template <class Epi, class Sched, bool ALIGN_EPI = false, bool SP2 = false>
; __device__ __forceinline__ void gemm_phase(PG8_LAS unsigned char* lds, const Gemm g, const Sched& S, const Epi& E) {
;     ...
; #pragma unroll
;         for (int a = 0; a < 2; ++a)
; #pragma unroll
;             for (int b = 0; b < 2; ++b)
; #pragma unroll
;                 for (int m = 0; m < 4; ++m)
; #pragma unroll
;                     for (int n = 0; n < 2; ++n) acc[a][b][m][n] = (f32x4){0.f, 0.f, 0.f, 0.f};
;         cur = nxt; cA = nA; cB = nB; ++ui;
.LBB0_330:
	s_add_u32 s34, s12, 0x100
	v_mov_b64_e32 v[2:3], 0
	s_addc_u32 s35, s13, 0
	s_mov_b32 s37, -2
	v_mov_b64_e32 v[4:5], 0
	v_mov_b64_e32 v[6:7], 0
	v_mov_b64_e32 v[8:9], 0
	v_mov_b64_e32 v[10:11], 0
	v_mov_b64_e32 v[12:13], 0
	v_mov_b64_e32 v[14:15], 0
	v_mov_b64_e32 v[16:17], 0
	v_mov_b64_e32 v[26:27], 0
	v_mov_b64_e32 v[28:29], 0
	v_mov_b64_e32 v[30:31], 0
	v_mov_b64_e32 v[32:33], 0
	v_mov_b64_e32 v[42:43], 0
	v_mov_b64_e32 v[44:45], 0
	v_mov_b64_e32 v[46:47], 0
	v_mov_b64_e32 v[48:49], 0
	v_mov_b64_e32 v[18:19], 0
	v_mov_b64_e32 v[20:21], 0
	v_mov_b64_e32 v[22:23], 0
	v_mov_b64_e32 v[24:25], 0
	v_mov_b64_e32 v[34:35], 0
	v_mov_b64_e32 v[36:37], 0
	v_mov_b64_e32 v[38:39], 0
	v_mov_b64_e32 v[40:41], 0
	v_mov_b64_e32 v[50:51], 0
	v_mov_b64_e32 v[52:53], 0
	v_mov_b64_e32 v[54:55], 0
	v_mov_b64_e32 v[56:57], 0
	v_mov_b64_e32 v[58:59], 0
	v_mov_b64_e32 v[60:61], 0
	v_mov_b64_e32 v[62:63], 0
	v_mov_b64_e32 v[64:65], 0
	v_mov_b64_e32 v[66:67], 0
	v_mov_b64_e32 v[68:69], 0
	v_mov_b64_e32 v[70:71], 0
	v_mov_b64_e32 v[72:73], 0
	v_mov_b64_e32 v[74:75], 0
	v_mov_b64_e32 v[76:77], 0
	v_mov_b64_e32 v[78:79], 0
	v_mov_b64_e32 v[80:81], 0
	v_mov_b64_e32 v[90:91], 0
	v_mov_b64_e32 v[92:93], 0
	v_mov_b64_e32 v[94:95], 0
	v_mov_b64_e32 v[96:97], 0
	v_mov_b64_e32 v[106:107], 0
	v_mov_b64_e32 v[108:109], 0
	v_mov_b64_e32 v[110:111], 0
	v_mov_b64_e32 v[112:113], 0
	v_mov_b64_e32 v[82:83], 0
	v_mov_b64_e32 v[84:85], 0
	v_mov_b64_e32 v[86:87], 0
	v_mov_b64_e32 v[88:89], 0
	v_mov_b64_e32 v[98:99], 0
	v_mov_b64_e32 v[100:101], 0
	v_mov_b64_e32 v[102:103], 0
	v_mov_b64_e32 v[104:105], 0
	v_mov_b64_e32 v[114:115], 0
	v_mov_b64_e32 v[116:117], 0
	v_mov_b64_e32 v[118:119], 0
	v_mov_b64_e32 v[120:121], 0
	v_mov_b64_e32 v[122:123], 0
	v_mov_b64_e32 v[124:125], 0
	v_mov_b64_e32 v[126:127], 0
	v_mov_b64_e32 v[128:129], 0

;     __device__ bool next(int i, pg8::Unit& u) const { const int j = i / 3, n = i - 3 * j; pg8::Unit t; if (!S4.next(j, t)) return false; u.pm = t.pm; u.pn = n * 4 + t.pn; return true; }
; template <class Epi, class Sched, bool ALIGN_EPI = false, bool SP2 = false>
; __device__ __forceinline__ void gemm_phase(PG8_LAS unsigned char* lds, const Gemm g, const Sched& S, const Epi& E) {
;     ...
;         const bool has_next = S.next(ui + 1, nxt);
;         const char* nA = has_next ? (const char*)g.A + (size_t)nxt.pm * tstepA + (size_t)(nxt.pn / g.adiv) * g.aoff * 2 : cA; const char* nB = has_next ? (const char*)g.Bt + (size_t)nxt.pn * tstepB : cB;
;         for (int t = 0; t < nt; t += 2) {
;             const bool last = (t == nt - 2);
;             const char* a1 = cA + (size_t)(t + 1) * kstep;
;             const char* a2 = last ? nA : cA + (size_t)(t + 2) * kstep; const char* b2 = last ? nB : cB + (size_t)(t + 2) * kstep;
;             const char* a3 = a2 + kstep; const char* b3 = b2 + kstep;
;     ...
; #pragma unroll
;         for (int a = 0; a < 2; ++a)
; #pragma unroll
;             for (int b = 0; b < 2; ++b)
; #pragma unroll
;                 for (int m = 0; m < 4; ++m)
; #pragma unroll
;                     for (int n = 0; n < 2; ++n) acc[a][b][m][n] = (f32x4){0.f, 0.f, 0.f, 0.f};
;         cur = nxt; cA = nA; cB = nB; ++ui;
.LBB0_736:
	s_ashr_i32 s9, s8, 31
	s_lshl_b64 s[10:11], s[8:9], 19
	s_add_u32 s10, s92, s10
	s_addc_u32 s11, s93, s11
	s_and_b64 s[12:13], s[38:39], exec
	s_cselect_b32 s9, s11, s15
	s_cselect_b32 s34, s10, s14
	s_ashr_i32 s7, s6, 31
	s_lshl_b64 s[12:13], s[6:7], 19
	v_readlane_b32 s18, v249, 34
	v_readlane_b32 s19, v249, 35
	s_add_u32 s12, s18, s12
	s_addc_u32 s13, s19, s13
	s_and_b64 s[18:19], s[38:39], exec
	s_mov_b32 s47, s35
	s_cselect_b32 s7, s13, s17
	s_cselect_b32 s35, s12, s16
	s_add_u32 s14, s14, 0x40080
	s_addc_u32 s15, s15, 0
	s_add_u32 s37, s16, 0x100
	v_mov_b64_e32 v[2:3], 0
	s_addc_u32 s42, s17, 0
	s_mov_b32 s43, -2
	v_mov_b64_e32 v[4:5], 0
	v_mov_b64_e32 v[6:7], 0
	v_mov_b64_e32 v[8:9], 0
	v_mov_b64_e32 v[18:19], 0
	v_mov_b64_e32 v[20:21], 0
	v_mov_b64_e32 v[22:23], 0
	v_mov_b64_e32 v[24:25], 0
	v_mov_b64_e32 v[34:35], 0
	v_mov_b64_e32 v[36:37], 0
	v_mov_b64_e32 v[38:39], 0
	v_mov_b64_e32 v[40:41], 0
	v_mov_b64_e32 v[50:51], 0
	v_mov_b64_e32 v[52:53], 0
	v_mov_b64_e32 v[54:55], 0
	v_mov_b64_e32 v[56:57], 0
	v_mov_b64_e32 v[10:11], 0
	v_mov_b64_e32 v[12:13], 0
	v_mov_b64_e32 v[14:15], 0
	v_mov_b64_e32 v[16:17], 0
	v_mov_b64_e32 v[26:27], 0
	v_mov_b64_e32 v[28:29], 0
	v_mov_b64_e32 v[30:31], 0
	v_mov_b64_e32 v[32:33], 0
	v_mov_b64_e32 v[42:43], 0
	v_mov_b64_e32 v[44:45], 0
	v_mov_b64_e32 v[46:47], 0
	v_mov_b64_e32 v[48:49], 0
	v_mov_b64_e32 v[58:59], 0
	v_mov_b64_e32 v[60:61], 0
	v_mov_b64_e32 v[62:63], 0
	v_mov_b64_e32 v[64:65], 0
	v_mov_b64_e32 v[66:67], 0
	v_mov_b64_e32 v[68:69], 0
	v_mov_b64_e32 v[70:71], 0
	v_mov_b64_e32 v[72:73], 0
	v_mov_b64_e32 v[82:83], 0
	v_mov_b64_e32 v[84:85], 0
	v_mov_b64_e32 v[86:87], 0
	v_mov_b64_e32 v[88:89], 0
	v_mov_b64_e32 v[98:99], 0
	v_mov_b64_e32 v[100:101], 0
	v_mov_b64_e32 v[102:103], 0
	v_mov_b64_e32 v[104:105], 0
	v_mov_b64_e32 v[114:115], 0
	v_mov_b64_e32 v[116:117], 0
	v_mov_b64_e32 v[118:119], 0
	v_mov_b64_e32 v[120:121], 0
	v_mov_b64_e32 v[74:75], 0
	v_mov_b64_e32 v[76:77], 0
	v_mov_b64_e32 v[78:79], 0
	v_mov_b64_e32 v[80:81], 0
	v_mov_b64_e32 v[90:91], 0
	v_mov_b64_e32 v[92:93], 0
	v_mov_b64_e32 v[94:95], 0
	v_mov_b64_e32 v[96:97], 0
	v_mov_b64_e32 v[106:107], 0
	v_mov_b64_e32 v[108:109], 0
	v_mov_b64_e32 v[110:111], 0
	v_mov_b64_e32 v[112:113], 0
	v_mov_b64_e32 v[122:123], 0
	v_mov_b64_e32 v[124:125], 0
	v_mov_b64_e32 v[126:127], 0
	v_mov_b64_e32 v[128:129], 0

;     __device__ bool next(int i, pg8::Unit& u) const { const int j = i / 3, n = i - 3 * j; pg8::Unit t; if (!S4.next(j, t)) return false; u.pm = t.pm; u.pn = n * 4 + t.pn; return true; }
; template <class Epi, class Sched, bool ALIGN_EPI = false, bool SP2 = false>
; __device__ __forceinline__ void gemm_phase(PG8_LAS unsigned char* lds, const Gemm g, const Sched& S, const Epi& E) {
;     ...
;         const bool has_next = S.next(ui + 1, nxt);
;         const char* nA = has_next ? (const char*)g.A + (size_t)nxt.pm * tstepA + (size_t)(nxt.pn / g.adiv) * g.aoff * 2 : cA; const char* nB = has_next ? (const char*)g.Bt + (size_t)nxt.pn * tstepB : cB;
;         for (int t = 0; t < nt; t += 2) {
;             const bool last = (t == nt - 2);
;             const char* a1 = cA + (size_t)(t + 1) * kstep;
;             const char* a2 = last ? nA : cA + (size_t)(t + 2) * kstep; const char* b2 = last ? nB : cB + (size_t)(t + 2) * kstep;
;             const char* a3 = a2 + kstep; const char* b3 = b2 + kstep;
;     ...
; #pragma unroll
;         for (int a = 0; a < 2; ++a)
; #pragma unroll
;             for (int b = 0; b < 2; ++b)
; #pragma unroll
;                 for (int m = 0; m < 4; ++m)
; #pragma unroll
;                     for (int n = 0; n < 2; ++n) acc[a][b][m][n] = (f32x4){0.f, 0.f, 0.f, 0.f};
;         cur = nxt; cA = nA; cB = nB; ++ui;
.LBB0_876:
	s_ashr_i32 s13, s12, 31
	s_lshl_b64 s[14:15], s[12:13], 19
	s_add_u32 s14, s27, s14
	s_addc_u32 s15, s28, s15
	s_and_b64 s[16:17], s[8:9], exec
	s_cselect_b32 s5, s15, s19
	s_cselect_b32 s13, s14, s18
	s_ashr_i32 s11, s10, 31
	s_lshl_b64 s[16:17], s[10:11], 19
	s_add_u32 s16, s0, s16
	s_addc_u32 s17, s1, s17
	s_and_b64 s[22:23], s[8:9], exec
	s_cselect_b32 s11, s17, s21
	s_cselect_b32 s39, s16, s20
	s_add_u32 s18, s18, 0x40080
	s_addc_u32 s19, s19, 0
	s_add_u32 s42, s20, 0x100
	v_mov_b64_e32 v[2:3], 0
	s_addc_u32 s43, s21, 0
	s_mov_b32 s44, -2
	v_mov_b64_e32 v[4:5], 0
	v_mov_b64_e32 v[6:7], 0
	v_mov_b64_e32 v[8:9], 0
	v_mov_b64_e32 v[10:11], 0
	v_mov_b64_e32 v[12:13], 0
	v_mov_b64_e32 v[14:15], 0
	v_mov_b64_e32 v[16:17], 0
	v_mov_b64_e32 v[22:23], 0
	v_mov_b64_e32 v[24:25], 0
	v_mov_b64_e32 v[30:31], 0
	v_mov_b64_e32 v[32:33], 0
	v_mov_b64_e32 v[38:39], 0
	v_mov_b64_e32 v[40:41], 0
	v_mov_b64_e32 v[46:47], 0
	v_mov_b64_e32 v[48:49], 0
	v_mov_b64_e32 v[18:19], 0
	v_mov_b64_e32 v[20:21], 0
	v_mov_b64_e32 v[26:27], 0
	v_mov_b64_e32 v[28:29], 0
	v_mov_b64_e32 v[34:35], 0
	v_mov_b64_e32 v[36:37], 0
	v_mov_b64_e32 v[42:43], 0
	v_mov_b64_e32 v[44:45], 0
	v_mov_b64_e32 v[50:51], 0
	v_mov_b64_e32 v[52:53], 0
	v_mov_b64_e32 v[54:55], 0
	v_mov_b64_e32 v[56:57], 0
	v_mov_b64_e32 v[58:59], 0
	v_mov_b64_e32 v[60:61], 0
	v_mov_b64_e32 v[62:63], 0
	v_mov_b64_e32 v[64:65], 0
	v_mov_b64_e32 v[66:67], 0
	v_mov_b64_e32 v[68:69], 0
	v_mov_b64_e32 v[70:71], 0
	v_mov_b64_e32 v[72:73], 0
	v_mov_b64_e32 v[74:75], 0
	v_mov_b64_e32 v[76:77], 0
	v_mov_b64_e32 v[78:79], 0
	v_mov_b64_e32 v[80:81], 0
	v_mov_b64_e32 v[86:87], 0
	v_mov_b64_e32 v[88:89], 0
	v_mov_b64_e32 v[94:95], 0
	v_mov_b64_e32 v[96:97], 0
	v_mov_b64_e32 v[102:103], 0
	v_mov_b64_e32 v[104:105], 0
	v_mov_b64_e32 v[110:111], 0
	v_mov_b64_e32 v[112:113], 0
	v_mov_b64_e32 v[82:83], 0
	v_mov_b64_e32 v[84:85], 0
	v_mov_b64_e32 v[90:91], 0
	v_mov_b64_e32 v[92:93], 0
	v_mov_b64_e32 v[98:99], 0
	v_mov_b64_e32 v[100:101], 0
	v_mov_b64_e32 v[106:107], 0
	v_mov_b64_e32 v[108:109], 0
	v_mov_b64_e32 v[114:115], 0
	v_mov_b64_e32 v[116:117], 0
	v_mov_b64_e32 v[118:119], 0
	v_mov_b64_e32 v[120:121], 0
	v_mov_b64_e32 v[122:123], 0
	v_mov_b64_e32 v[124:125], 0
	v_mov_b64_e32 v[126:127], 0
	v_mov_b64_e32 v[128:129], 0

;     __device__ bool next(int i, pg8::Unit& u) const { const int j = i / 3, n = i - 3 * j; pg8::Unit t; if (!S4.next(j, t)) return false; u.pm = t.pm; u.pn = n * 4 + t.pn; return true; }
; template <class Epi, class Sched, bool ALIGN_EPI = false, bool SP2 = false>
; __device__ __forceinline__ void gemm_phase(PG8_LAS unsigned char* lds, const Gemm g, const Sched& S, const Epi& E) {
;     ...
;         const bool has_next = S.next(ui + 1, nxt);
;         const char* nA = has_next ? (const char*)g.A + (size_t)nxt.pm * tstepA + (size_t)(nxt.pn / g.adiv) * g.aoff * 2 : cA; const char* nB = has_next ? (const char*)g.Bt + (size_t)nxt.pn * tstepB : cB;
;         for (int t = 0; t < nt; t += 2) {
;             const bool last = (t == nt - 2);
;             const char* a1 = cA + (size_t)(t + 1) * kstep;
;             const char* a2 = last ? nA : cA + (size_t)(t + 2) * kstep; const char* b2 = last ? nB : cB + (size_t)(t + 2) * kstep;
;             const char* a3 = a2 + kstep; const char* b3 = b2 + kstep;
;     ...
; #pragma unroll
;         for (int a = 0; a < 2; ++a)
; #pragma unroll
;             for (int b = 0; b < 2; ++b)
; #pragma unroll
;                 for (int m = 0; m < 4; ++m)
; #pragma unroll
;                     for (int n = 0; n < 2; ++n) acc[a][b][m][n] = (f32x4){0.f, 0.f, 0.f, 0.f};
;         cur = nxt; cA = nA; cB = nB; ++ui;
.LBB0_1245:
	s_ashr_i32 s9, s8, 31
	s_lshl_b64 s[10:11], s[8:9], 19
	s_add_u32 s10, s92, s10
	s_addc_u32 s11, s93, s11
	s_and_b64 s[12:13], s[0:1], exec
	s_cselect_b32 s9, s11, s15
	s_cselect_b32 s30, s10, s14
	s_ashr_i32 s7, s6, 31
	s_lshl_b64 s[12:13], s[6:7], 19
	v_readlane_b32 s18, v249, 36
	v_readlane_b32 s19, v249, 37
	s_add_u32 s12, s18, s12
	s_addc_u32 s13, s19, s13
	s_and_b64 s[18:19], s[0:1], exec
	s_cselect_b32 s7, s13, s17
	s_cselect_b32 s31, s12, s16
	s_add_u32 s14, s14, 0x40080
	s_addc_u32 s15, s15, 0
	s_add_u32 s33, s16, 0x100
	v_mov_b64_e32 v[2:3], 0
	s_addc_u32 s34, s17, 0
	s_mov_b32 s35, -2
	v_mov_b64_e32 v[4:5], 0
	v_mov_b64_e32 v[6:7], 0
	v_mov_b64_e32 v[8:9], 0
	v_mov_b64_e32 v[18:19], 0
	v_mov_b64_e32 v[20:21], 0
	v_mov_b64_e32 v[22:23], 0
	v_mov_b64_e32 v[24:25], 0
	v_mov_b64_e32 v[34:35], 0
	v_mov_b64_e32 v[36:37], 0
	v_mov_b64_e32 v[38:39], 0
	v_mov_b64_e32 v[40:41], 0
	v_mov_b64_e32 v[50:51], 0
	v_mov_b64_e32 v[52:53], 0
	v_mov_b64_e32 v[54:55], 0
	v_mov_b64_e32 v[56:57], 0
	v_mov_b64_e32 v[10:11], 0
	v_mov_b64_e32 v[12:13], 0
	v_mov_b64_e32 v[14:15], 0
	v_mov_b64_e32 v[16:17], 0
	v_mov_b64_e32 v[26:27], 0
	v_mov_b64_e32 v[28:29], 0
	v_mov_b64_e32 v[30:31], 0
	v_mov_b64_e32 v[32:33], 0
	v_mov_b64_e32 v[42:43], 0
	v_mov_b64_e32 v[44:45], 0
	v_mov_b64_e32 v[46:47], 0
	v_mov_b64_e32 v[48:49], 0
	v_mov_b64_e32 v[58:59], 0
	v_mov_b64_e32 v[60:61], 0
	v_mov_b64_e32 v[62:63], 0
	v_mov_b64_e32 v[64:65], 0
	v_mov_b64_e32 v[66:67], 0
	v_mov_b64_e32 v[68:69], 0
	v_mov_b64_e32 v[70:71], 0
	v_mov_b64_e32 v[72:73], 0
	v_mov_b64_e32 v[82:83], 0
	v_mov_b64_e32 v[84:85], 0
	v_mov_b64_e32 v[86:87], 0
	v_mov_b64_e32 v[88:89], 0
	v_mov_b64_e32 v[98:99], 0
	v_mov_b64_e32 v[100:101], 0
	v_mov_b64_e32 v[102:103], 0
	v_mov_b64_e32 v[104:105], 0
	v_mov_b64_e32 v[114:115], 0
	v_mov_b64_e32 v[116:117], 0
	v_mov_b64_e32 v[118:119], 0
	v_mov_b64_e32 v[120:121], 0
	v_mov_b64_e32 v[74:75], 0
	v_mov_b64_e32 v[76:77], 0
	v_mov_b64_e32 v[78:79], 0
	v_mov_b64_e32 v[80:81], 0
	v_mov_b64_e32 v[90:91], 0
	v_mov_b64_e32 v[92:93], 0
	v_mov_b64_e32 v[94:95], 0
	v_mov_b64_e32 v[96:97], 0
	v_mov_b64_e32 v[106:107], 0
	v_mov_b64_e32 v[108:109], 0
	v_mov_b64_e32 v[110:111], 0
	v_mov_b64_e32 v[112:113], 0
	v_mov_b64_e32 v[122:123], 0
	v_mov_b64_e32 v[124:125], 0
	v_mov_b64_e32 v[126:127], 0
	v_mov_b64_e32 v[128:129], 0

;     __device__ bool next(int i, pg8::Unit& u) const { const int j = i / 3, n = i - 3 * j; pg8::Unit t; if (!S4.next(j, t)) return false; u.pm = t.pm; u.pn = n * 4 + t.pn; return true; }
; template <class Epi, class Sched, bool ALIGN_EPI = false, bool SP2 = false>
; __device__ __forceinline__ void gemm_phase(PG8_LAS unsigned char* lds, const Gemm g, const Sched& S, const Epi& E) {
;     ...
;         const bool has_next = S.next(ui + 1, nxt);
;         const char* nA = has_next ? (const char*)g.A + (size_t)nxt.pm * tstepA + (size_t)(nxt.pn / g.adiv) * g.aoff * 2 : cA; const char* nB = has_next ? (const char*)g.Bt + (size_t)nxt.pn * tstepB : cB;
;         for (int t = 0; t < nt; t += 2) {
;             const bool last = (t == nt - 2);
;             const char* a1 = cA + (size_t)(t + 1) * kstep;
;             const char* a2 = last ? nA : cA + (size_t)(t + 2) * kstep; const char* b2 = last ? nB : cB + (size_t)(t + 2) * kstep;
;             const char* a3 = a2 + kstep; const char* b3 = b2 + kstep;
;     ...
; #pragma unroll
;         for (int a = 0; a < 2; ++a)
; #pragma unroll
;             for (int b = 0; b < 2; ++b)
; #pragma unroll
;                 for (int m = 0; m < 4; ++m)
; #pragma unroll
;                     for (int n = 0; n < 2; ++n) acc[a][b][m][n] = (f32x4){0.f, 0.f, 0.f, 0.f};
;         cur = nxt; cA = nA; cB = nB; ++ui;
.LBB0_1319:
	s_ashr_i32 s9, s8, 31
	s_lshl_b64 s[12:13], s[8:9], 18
	v_readlane_b32 s18, v249, 38
	v_readlane_b32 s19, v249, 39
	s_add_u32 s12, s18, s12
	s_addc_u32 s13, s19, s13
	s_and_b64 s[0:1], s[0:1], exec
	s_cselect_b32 s9, s13, s17
	s_cselect_b32 s31, s12, s16
	s_add_u32 s33, s16, 0x100
	v_mov_b64_e32 v[2:3], 0
	s_addc_u32 s34, s17, 0
	s_mov_b32 s35, -2
	v_mov_b64_e32 v[4:5], 0
	v_mov_b64_e32 v[6:7], 0
	v_mov_b64_e32 v[8:9], 0
	v_mov_b64_e32 v[18:19], 0
	v_mov_b64_e32 v[20:21], 0
	v_mov_b64_e32 v[22:23], 0
	v_mov_b64_e32 v[24:25], 0
	v_mov_b64_e32 v[34:35], 0
	v_mov_b64_e32 v[36:37], 0
	v_mov_b64_e32 v[38:39], 0
	v_mov_b64_e32 v[40:41], 0
	v_mov_b64_e32 v[50:51], 0
	v_mov_b64_e32 v[52:53], 0
	v_mov_b64_e32 v[54:55], 0
	v_mov_b64_e32 v[56:57], 0
	v_mov_b64_e32 v[10:11], 0
	v_mov_b64_e32 v[12:13], 0
	v_mov_b64_e32 v[14:15], 0
	v_mov_b64_e32 v[16:17], 0
	v_mov_b64_e32 v[26:27], 0
	v_mov_b64_e32 v[28:29], 0
	v_mov_b64_e32 v[30:31], 0
	v_mov_b64_e32 v[32:33], 0
	v_mov_b64_e32 v[42:43], 0
	v_mov_b64_e32 v[44:45], 0
	v_mov_b64_e32 v[46:47], 0
	v_mov_b64_e32 v[48:49], 0
	v_mov_b64_e32 v[58:59], 0
	v_mov_b64_e32 v[60:61], 0
	v_mov_b64_e32 v[62:63], 0
	v_mov_b64_e32 v[64:65], 0
	v_mov_b64_e32 v[66:67], 0
	v_mov_b64_e32 v[68:69], 0
	v_mov_b64_e32 v[70:71], 0
	v_mov_b64_e32 v[72:73], 0
	v_mov_b64_e32 v[82:83], 0
	v_mov_b64_e32 v[84:85], 0
	v_mov_b64_e32 v[86:87], 0
	v_mov_b64_e32 v[88:89], 0
	v_mov_b64_e32 v[98:99], 0
	v_mov_b64_e32 v[100:101], 0
	v_mov_b64_e32 v[102:103], 0
	v_mov_b64_e32 v[104:105], 0
	v_mov_b64_e32 v[114:115], 0
	v_mov_b64_e32 v[116:117], 0
	v_mov_b64_e32 v[118:119], 0
	v_mov_b64_e32 v[120:121], 0
	v_mov_b64_e32 v[74:75], 0
	v_mov_b64_e32 v[76:77], 0
	v_mov_b64_e32 v[78:79], 0
	v_mov_b64_e32 v[80:81], 0
	v_mov_b64_e32 v[90:91], 0
	v_mov_b64_e32 v[92:93], 0
	v_mov_b64_e32 v[94:95], 0
	v_mov_b64_e32 v[96:97], 0
	v_mov_b64_e32 v[106:107], 0
	v_mov_b64_e32 v[108:109], 0
	v_mov_b64_e32 v[110:111], 0
	v_mov_b64_e32 v[112:113], 0
	v_mov_b64_e32 v[122:123], 0
	v_mov_b64_e32 v[124:125], 0
	v_mov_b64_e32 v[126:127], 0
	v_mov_b64_e32 v[128:129], 0

;     __device__ bool next(int i, pg8::Unit& u) const { const int j = i / 3, n = i - 3 * j; pg8::Unit t; if (!S4.next(j, t)) return false; u.pm = t.pm; u.pn = n * 4 + t.pn; return true; }
; template <class Epi, class Sched, bool ALIGN_EPI = false, bool SP2 = false>
; __device__ __forceinline__ void gemm_phase(PG8_LAS unsigned char* lds, const Gemm g, const Sched& S, const Epi& E) {
;     ...
;         const bool has_next = S.next(ui + 1, nxt);
;         const char* nA = has_next ? (const char*)g.A + (size_t)nxt.pm * tstepA + (size_t)(nxt.pn / g.adiv) * g.aoff * 2 : cA; const char* nB = has_next ? (const char*)g.Bt + (size_t)nxt.pn * tstepB : cB;
;         for (int t = 0; t < nt; t += 2) {
;             const bool last = (t == nt - 2);
;             const char* a1 = cA + (size_t)(t + 1) * kstep;
;             const char* a2 = last ? nA : cA + (size_t)(t + 2) * kstep; const char* b2 = last ? nB : cB + (size_t)(t + 2) * kstep;
;             const char* a3 = a2 + kstep; const char* b3 = b2 + kstep;
;     ...
; #pragma unroll
;         for (int a = 0; a < 2; ++a)
; #pragma unroll
;             for (int b = 0; b < 2; ++b)
; #pragma unroll
;                 for (int m = 0; m < 4; ++m)
; #pragma unroll
;                     for (int n = 0; n < 2; ++n) acc[a][b][m][n] = (f32x4){0.f, 0.f, 0.f, 0.f};
;         cur = nxt; cA = nA; cB = nB; ++ui;
.LBB0_1457:
	s_ashr_i32 s9, s8, 31
	s_lshl_b64 s[10:11], s[8:9], 19
	s_add_u32 s10, s92, s10
	s_addc_u32 s11, s93, s11
	s_and_b64 s[12:13], s[0:1], exec
	s_cselect_b32 s9, s11, s15
	s_cselect_b32 s30, s10, s14
	s_ashr_i32 s7, s6, 31
	s_lshl_b64 s[12:13], s[6:7], 19
	v_readlane_b32 s18, v249, 44
	v_readlane_b32 s19, v249, 45
	s_add_u32 s12, s18, s12
	s_addc_u32 s13, s19, s13
	s_and_b64 s[18:19], s[0:1], exec
	s_cselect_b32 s7, s13, s17
	s_cselect_b32 s31, s12, s16
	s_add_u32 s14, s14, 0x40080
	s_addc_u32 s15, s15, 0
	s_add_u32 s33, s16, 0x100
	v_mov_b64_e32 v[2:3], 0
	s_addc_u32 s34, s17, 0
	s_mov_b32 s35, -2
	v_mov_b64_e32 v[4:5], 0
	v_mov_b64_e32 v[6:7], 0
	v_mov_b64_e32 v[8:9], 0
	v_mov_b64_e32 v[10:11], 0
	v_mov_b64_e32 v[12:13], 0
	v_mov_b64_e32 v[14:15], 0
	v_mov_b64_e32 v[16:17], 0
	v_mov_b64_e32 v[26:27], 0
	v_mov_b64_e32 v[28:29], 0
	v_mov_b64_e32 v[30:31], 0
	v_mov_b64_e32 v[32:33], 0
	v_mov_b64_e32 v[42:43], 0
	v_mov_b64_e32 v[44:45], 0
	v_mov_b64_e32 v[46:47], 0
	v_mov_b64_e32 v[48:49], 0
	v_mov_b64_e32 v[18:19], 0
	v_mov_b64_e32 v[20:21], 0
	v_mov_b64_e32 v[22:23], 0
	v_mov_b64_e32 v[24:25], 0
	v_mov_b64_e32 v[34:35], 0
	v_mov_b64_e32 v[36:37], 0
	v_mov_b64_e32 v[38:39], 0
	v_mov_b64_e32 v[40:41], 0
	v_mov_b64_e32 v[50:51], 0
	v_mov_b64_e32 v[52:53], 0
	v_mov_b64_e32 v[54:55], 0
	v_mov_b64_e32 v[56:57], 0
	v_mov_b64_e32 v[58:59], 0
	v_mov_b64_e32 v[60:61], 0
	v_mov_b64_e32 v[62:63], 0
	v_mov_b64_e32 v[64:65], 0
	v_mov_b64_e32 v[66:67], 0
	v_mov_b64_e32 v[68:69], 0
	v_mov_b64_e32 v[70:71], 0
	v_mov_b64_e32 v[72:73], 0
	v_mov_b64_e32 v[74:75], 0
	v_mov_b64_e32 v[76:77], 0
	v_mov_b64_e32 v[78:79], 0
	v_mov_b64_e32 v[80:81], 0
	v_mov_b64_e32 v[90:91], 0
	v_mov_b64_e32 v[92:93], 0
	v_mov_b64_e32 v[94:95], 0
	v_mov_b64_e32 v[96:97], 0
	v_mov_b64_e32 v[106:107], 0
	v_mov_b64_e32 v[108:109], 0
	v_mov_b64_e32 v[110:111], 0
	v_mov_b64_e32 v[112:113], 0
	v_mov_b64_e32 v[82:83], 0
	v_mov_b64_e32 v[84:85], 0
	v_mov_b64_e32 v[86:87], 0
	v_mov_b64_e32 v[88:89], 0
	v_mov_b64_e32 v[98:99], 0
	v_mov_b64_e32 v[100:101], 0
	v_mov_b64_e32 v[102:103], 0
	v_mov_b64_e32 v[104:105], 0
	v_mov_b64_e32 v[114:115], 0
	v_mov_b64_e32 v[116:117], 0
	v_mov_b64_e32 v[118:119], 0
	v_mov_b64_e32 v[120:121], 0
	v_mov_b64_e32 v[122:123], 0
	v_mov_b64_e32 v[124:125], 0
	v_mov_b64_e32 v[126:127], 0
	v_mov_b64_e32 v[128:129], 0
